# cv32 + K-block-fastest conversion item order also for w_out_a/w_out_b/w_o/w_down (contiguous bf16 destination writes for every weight kind)
# baseline (speedup 1.0000x reference)
.Lcv_d0_n32:
	s_cmp_eq_u32 s29, 0xb0
	s_cbranch_scc1 .Lcv_d0_n32dn
	s_cmp_eq_u32 s29, 0x38
	s_cselect_b32 s48, 4, 5
	s_lshr_b32 s35, s13, s48
	s_lshl_b32 s49, s35, s48
	s_sub_u32 s14, s13, s49
	s_branch .Lcv_d0_n32d
.Lcv_d0_n32dn:
	s_mul_hi_u32 s35, s13, 0x2e8ba2f
	s_mul_i32 s49, s35, 88
	s_sub_u32 s14, s13, s49
.Lcv_d0_n32d:
	s_lshl_b32 s39, s35, 6
	s_branch .Lcv_d0_common
